# NSA item prologue de-serialised: second compressed-KV staging batch and bias-table loads issued together with the first batch, one wait
# baseline (speedup 1.0000x reference)
; DI void nsa_attn_phase(int wv, const P& p_, LAS unsigned char* lds) {
;     ...
;     { KVRegs ka, kb; const bf16_t* kcg = (const bf16_t*)(p.ws + WS_KC) + (size_t)((b * 4 + g) * 256) * 64; const bf16_t* vcg = (const bf16_t*)(p.ws + WS_VC) + (size_t)((b * 4 + g) * 256) * 64;
;       kv_load(ka, kcg, vcg, 64, tid); if (nct > 1) kv_load(kb, kcg + 64 * 64, vcg + 64 * 64, 64, tid);
;       kv_store(ka, KC, VCT, 260, 0, tid); if (nct > 1) kv_store(kb, KC + 64 * KS_STRIDE, VCT, 260, 64, tid);
;       if (nct > 2) { kv_load(ka, kcg + 128 * 64, vcg + 128 * 64, 64, tid); if (nct > 3) kv_load(kb, kcg + 192 * 64, vcg + 192 * 64, 64, tid);
;         kv_store(ka, KC + 128 * KS_STRIDE, VCT, 260, 128, tid); if (nct > 3) kv_store(kb, KC + 192 * KS_STRIDE, VCT, 260, 192, tid); } }
;     for (int i = tid; i < 4 * 132; i += 512) BT[i] = ((const float*)(p.ws + C_BTAB))[g * 4 * 132 + i] * 1.4426950408889634f;
.LBB0_662:
	s_cmpk_lt_i32 s10, 0x80
	s_cbranch_scc1 .Lnsa_pro_nob2
	v_ashrrev_i32_e32 v8, 3, v130
	v_ashrrev_i32_e32 v9, 31, v8
	v_lshlrev_b64 v[8:9], 7, v[8:9]
	v_lshlrev_b32_e32 v12, 4, v130
	v_and_b32_e32 v12, 0x70, v12
	v_mov_b32_e32 v13, v32
	v_lshl_add_u64 v[10:11], s[6:7], 0, v[8:9]
	v_lshl_add_u64 v[10:11], v[10:11], 0, v[12:13]
	v_lshl_add_u64 v[8:9], s[0:1], 0, v[8:9]
	v_lshl_add_u64 v[8:9], v[8:9], 0, v[12:13]
	s_mov_b64 s[98:99], 0x4000
	v_lshl_add_u64 v[248:249], v[10:11], 0, s[98:99]
	v_lshl_add_u64 v[250:251], v[8:9], 0, s[98:99]
	global_load_dwordx4 v[216:219], v[248:249], off
	global_load_dwordx4 v[220:223], v[250:251], off
	s_cmpk_lt_u32 s13, 0xc0
	s_cbranch_scc1 .Lnsa_pro_nob2
	s_mov_b64 s[98:99], 0x6000
	v_lshl_add_u64 v[248:249], v[10:11], 0, s[98:99]
	v_lshl_add_u64 v[250:251], v[8:9], 0, s[98:99]
	global_load_dwordx4 v[224:227], v[248:249], off
	global_load_dwordx4 v[244:247], v[250:251], off
.Lnsa_pro_nob2:
	s_mul_i32 s98, s12, 0x210
	v_add_u32_e32 v8, s98, v130
	v_add_u32_e32 v10, 0x200, v8
	v_ashrrev_i32_e32 v9, 31, v8
	v_ashrrev_i32_e32 v11, 31, v10
	v_lshl_add_u64 v[8:9], v[8:9], 2, s[28:29]
	v_lshl_add_u64 v[10:11], v[10:11], 2, s[28:29]
	s_lshr_b32 s98, s94, 3
	s_and_b32 s98, s98, 3
	s_mulk_i32 s98, 0x840
	s_add_u32 s98, s46, s98
	s_addc_u32 s99, s47, 0
	v_mov_b32_e32 v12, v130
	v_mov_b32_e32 v13, v32
	v_lshl_add_u64 v[12:13], v[12:13], 2, s[98:99]
	v_cmp_gt_u32_e32 vcc, 16, v130
	s_and_saveexec_b64 s[100:101], vcc
	global_load_dword v248, v[8:9], off
	global_load_dword v249, v[10:11], off
	s_andn2_b64 exec, s[100:101], vcc
	global_load_dword v250, v[12:13], off
	s_mov_b64 exec, s[100:101]
	v_mov_b32_e32 v8, v130
	s_nop 0
	v_lshlrev_b32_e32 v10, 3, v8
	v_ashrrev_i32_e32 v9, 3, v8
	v_and_b32_e32 v10, 56, v10
	v_mul_lo_u32 v11, v9, s90
	v_lshlrev_b32_e32 v12, 1, v10
	v_add3_u32 v11, 0, v11, v12
	s_waitcnt vmcnt(1)
	ds_write_b128 v11, v[4:7] offset:35840
	v_and_b32_e32 v4, 8, v8
	v_cmp_eq_u32_e32 vcc, 0, v4
	v_mov_b32_e32 v7, v32
	v_lshrrev_b32_e32 v4, 1, v4
	s_waitcnt vmcnt(0)
	v_cndmask_b32_e32 v5, v0, v2, vcc
	v_cndmask_b32_e32 v6, v1, v3, vcc
	v_or_b32_e32 v4, v10, v4
	v_mov_b32_dpp v7, v5 row_ror:8 row_mask:0xf bank_mask:0xf
	v_mov_b32_e32 v5, v32
	v_cndmask_b32_e32 v2, v2, v7, vcc
	v_mul_u32_u24_e32 v4, 0x208, v4
	v_mov_b32_dpp v5, v6 row_ror:8 row_mask:0xf bank_mask:0xf
	v_cndmask_b32_e32 v1, v5, v1, vcc
	v_cndmask_b32_e32 v3, v3, v5, vcc
	v_lshlrev_b32_e32 v5, 1, v9
	v_and_b32_e32 v5, -4, v5
	v_cndmask_b32_e32 v0, v7, v0, vcc
	v_add3_u32 v4, s44, v4, v5
	v_lshlrev_b32_e32 v5, 16, v2
	v_and_or_b32 v5, v0, s89, v5
	v_lshrrev_b32_e32 v0, 16, v0
	v_and_or_b32 v0, v2, s88, v0
	ds_write2_b32 v4, v5, v0 offset1:130
	v_lshlrev_b32_e32 v0, 16, v3
	v_and_or_b32 v0, v1, s89, v0
	v_lshrrev_b32_e32 v1, 16, v1
	v_and_or_b32 v1, v3, s88, v1
	v_add_u32_e32 v2, 0x400, v4
	s_andn2_b64 vcc, exec, s[8:9]
	ds_write2_b32 v2, v0, v1 offset0:4 offset1:134
	s_cbranch_vccnz .LBB0_664
	v_mov_b32_e32 v0, v130
	v_mov_b32_e32 v5, v32
	v_lshlrev_b32_e32 v2, 3, v0
	v_ashrrev_i32_e32 v1, 3, v0
	v_and_b32_e32 v2, 56, v2
	v_mul_lo_u32 v3, v1, s90
	v_lshlrev_b32_e32 v4, 1, v2
	v_and_b32_e32 v0, 8, v0
	v_add3_u32 v3, 0, v3, v4
	v_cmp_eq_u32_e32 vcc, 0, v0
	ds_write_b128 v3, v[98:101] offset:45056
	v_lshrrev_b32_e32 v0, 1, v0
	v_cndmask_b32_e32 v3, v102, v104, vcc
	v_cndmask_b32_e32 v4, v103, v105, vcc
	v_or_b32_e32 v0, v2, v0
	v_mov_b32_dpp v5, v3 row_ror:8 row_mask:0xf bank_mask:0xf
	v_mov_b32_e32 v3, v32
	v_lshlrev_b32_e32 v1, 1, v1
	v_mul_u32_u24_e32 v0, 0x208, v0
	v_mov_b32_dpp v3, v4 row_ror:8 row_mask:0xf bank_mask:0xf
	v_cndmask_b32_e32 v4, v5, v102, vcc
	v_cndmask_b32_e32 v5, v104, v5, vcc
	v_and_b32_e32 v1, -4, v1
	v_add3_u32 v0, s44, v0, v1
	v_lshlrev_b32_e32 v1, 16, v5
	v_lshrrev_b32_e32 v2, 16, v4
	v_cndmask_b32_e32 v6, v3, v103, vcc
	v_cndmask_b32_e32 v3, v105, v3, vcc
	v_and_or_b32 v1, v4, s89, v1
	v_and_or_b32 v2, v5, s88, v2
	ds_write2_b32 v0, v1, v2 offset0:32 offset1:162
	v_lshlrev_b32_e32 v1, 16, v3
	v_lshrrev_b32_e32 v2, 16, v6
	v_and_or_b32 v1, v6, s89, v1
	v_and_or_b32 v2, v3, s88, v2
	v_add_u32_e32 v0, 0x400, v0
	ds_write2_b32 v0, v1, v2 offset0:36 offset1:166
.LBB0_664:
	s_cmpk_lt_i32 s10, 0x80
	s_cbranch_scc1 .LBB0_669
	s_cmpk_gt_u32 s13, 0xbf
	s_cselect_b64 s[8:9], -1, 0
	v_mov_b32_e32 v4, v216
	v_mov_b32_e32 v5, v217
	v_mov_b32_e32 v6, v218
	v_mov_b32_e32 v7, v219
	v_mov_b32_e32 v0, v220
	v_mov_b32_e32 v1, v221
	v_mov_b32_e32 v2, v222
	v_mov_b32_e32 v3, v223
	s_cmpk_lt_u32 s13, 0xc0
	s_cbranch_scc1 .LBB0_667
	v_mov_b32_e32 v98, v224
	v_mov_b32_e32 v99, v225
	v_mov_b32_e32 v100, v226
	v_mov_b32_e32 v101, v227
	v_mov_b32_e32 v102, v244
	v_mov_b32_e32 v103, v245
	v_mov_b32_e32 v104, v246
	v_mov_b32_e32 v105, v247

; DI void nsa_attn_phase(int wv, const P& p_, LAS unsigned char* lds) {
;     ...
;     for (int i = tid; i < 4 * 132; i += 512) BT[i] = ((const float*)(p.ws + C_BTAB))[g * 4 * 132 + i] * 1.4426950408889634f;
.LBB0_672:
	v_add_u32_e32 v6, s14, v0
	v_add_u32_e32 v8, s15, v1
	v_ashrrev_i32_e32 v7, 31, v6
	v_ashrrev_i32_e32 v9, 31, v8
	v_lshl_add_u64 v[6:7], v[6:7], 2, s[28:29]
	v_lshl_add_u64 v[8:9], v[8:9], 2, s[28:29]
	v_mov_b32_e32 v6, v248
	s_nop 0
	v_mov_b32_e32 v7, v249
	v_add_u32_e32 v5, -2, v5
	v_add_u32_e32 v8, 0xfffff800, v4
	v_cmp_eq_u32_e32 vcc, 0, v5
	v_add_u32_e32 v1, 0x400, v1
	v_add_u32_e32 v0, 0x400, v0
	s_or_b64 s[8:9], vcc, s[8:9]
	s_waitcnt vmcnt(0)
	v_pk_mul_f32 v[6:7], v[6:7], s[16:17] op_sel_hi:[1,0]
	ds_write_b32 v8, v6
	ds_write_b32 v4, v7
	v_add_u32_e32 v4, 0x1000, v4
	s_andn2_b64 exec, exec, s[8:9]
	s_cbranch_execnz .LBB0_672
	s_or_b64 exec, exec, s[8:9]
	v_cmp_ne_u32_e32 vcc, v2, v3
	v_lshl_add_u32 v0, v3, 9, v130
	s_orn2_b64 s[8:9], vcc, exec

; DI void nsa_attn_phase(int wv, const P& p_, LAS unsigned char* lds) {
;     ...
;     for (int i = tid; i < 4 * 132; i += 512) BT[i] = ((const float*)(p.ws + C_BTAB))[g * 4 * 132 + i] * 1.4426950408889634f;
.LBB0_676:
	v_mov_b32_e32 v4, v250
	v_add_u32_e32 v2, 0x200, v2
	v_cmp_lt_i32_e32 vcc, 15, v2
	v_lshl_add_u64 v[0:1], v[0:1], 0, s[18:19]
	s_or_b64 s[6:7], vcc, s[6:7]
	s_waitcnt vmcnt(0)
	v_mul_f32_e32 v4, 0x3fb8aa3b, v4
	ds_write_b32 v3, v4
	v_add_u32_e32 v3, 0x800, v3
	s_andn2_b64 exec, exec, s[6:7]
	s_cbranch_execnz .LBB0_676
